# combined: stagger + w_out epilogue loads in flight + filter-stage loads hoisted + weight-convert tile loads paired + XCD barrier at first seam
# speedup vs baseline: 1.0069x; 1.0069x over previous
; DI int otid() { int t = threadIdx.x; asm volatile("" : "+v"(t)); return t; }
; DI void cvt_tile(const float* __restrict__ src, int ldn, h16* __restrict__ dst, int ldk, int k0, int n0, float* t) {
;   const int tid = otid();
;   {
;     const int r = tid >> 4, c4 = tid & 15;
; #pragma unroll
;     for (int i = 0; i < 2; ++i) {
;       const int k = r + 32 * i;
;       const float4 v = *(const float4*)(src + (size_t)(k0 + k) * ldn + n0 + c4 * 4);
;       t[k * 65 + c4 * 4 + 0] = v.x; t[k * 65 + c4 * 4 + 1] = v.y; t[k * 65 + c4 * 4 + 2] = v.z; t[k * 65 + c4 * 4 + 3] = v.w;
;     }
;   }
;   __syncthreads();
;   {
;     const int n = tid >> 3, kc = tid & 7;
;     half8 o;
; #pragma unroll
;     for (int j = 0; j < 8; ++j) o[j] = (h16)t[(kc * 8 + j) * 65 + n];
;     *(half8*)(dst + (size_t)(n0 + n) * ldk + k0 + kc * 8) = o;
;   }
;   __syncthreads();
; }
; DI void cvt_layer_weights(const Params& P, int layer, int t0, int step, char* smem) {
;     ...
;     } else if (t < 2112 + 384) {
;       const int u = t - 2112, br = u >> 7, v = u & 127;
;       cvt_tile(P.w_branch + ((size_t)layer * 3 + br) * WB * D, D, wbrT + (size_t)br * D * LDY, LDY, (v & 7) * 64, (v >> 3) * 64, (float*)smem);
;     } else {
;       const int u = t - 2112 - 384;
;       cvt_tile(P.w_out + (size_t)layer * D * D, D, woutT, LDH, (u & 15) * 64, (u >> 4) * 64, (float*)smem);
;     }
.LBB0_116:
	s_cmpk_gt_i32 s70, 0x83f
	s_mov_b64 s[2:3], -1
	s_cbranch_scc0 .LBB0_122
	s_cmpk_gt_u32 s70, 0x9bf
	s_cbranch_scc0 .LBB0_119
	s_and_b32 s3, s96, 0x7fffffc0
	s_add_i32 s84, s3, 0xffffd900
	v_mov_b32_e32 v8, v208
	s_and_b32 s2, s97, 0x3c0
	s_lshl_b64 s[24:25], s[84:85], 2
	v_ashrrev_i32_e32 v2, 4, v8
	s_add_u32 s24, s51, s24
	v_lshlrev_b32_e32 v0, 4, v8
	v_add_u32_e32 v6, s2, v2
	s_addc_u32 s25, s74, s25
	v_and_b32_e32 v128, 0xf0, v0
	v_ashrrev_i32_e32 v7, 31, v6
	v_lshl_add_u64 v[4:5], s[24:25], 0, v[128:129]
	v_lshlrev_b64 v[0:1], 12, v[6:7]
	s_movk_i32 s3, 0x104
	v_lshl_add_u64 v[0:1], v[4:5], 0, v[0:1]
	v_mul_lo_u32 v2, v2, s3
	v_add3_u32 v7, 0, v128, v2
	global_load_dwordx4 v[0:3], v[0:1], off
	v_add_u32_e32 v10, 32, v6
	v_ashrrev_i32_e32 v11, 31, v10
	v_lshlrev_b64 v[10:11], 12, v[10:11]
	v_lshl_add_u64 v[10:11], v[4:5], 0, v[10:11]
	global_load_dwordx4 v[12:15], v[10:11], off
	v_ashrrev_i32_e32 v9, 3, v8
	s_waitcnt vmcnt(0)
	ds_write2_b32 v7, v0, v1 offset1:1
	ds_write2_b32 v7, v2, v3 offset0:2 offset1:3
	v_add_u32_e32 v4, 0x2080, v7
	s_waitcnt vmcnt(0)
	ds_write2_b32 v4, v12, v13 offset1:1
	v_add_u32_e32 v0, 0x2088, v7
	ds_write2_b32 v0, v14, v15 offset1:1
	v_lshlrev_b32_e32 v0, 3, v8
	v_and_b32_e32 v8, 56, v0
	v_lshlrev_b32_e32 v0, 2, v9
	v_mul_u32_u24_e32 v1, 0x104, v8
	v_add3_u32 v2, 0, v0, v1
	s_waitcnt lgkmcnt(0)
	s_barrier
	ds_read2_b32 v[4:5], v2 offset1:65
	ds_read2_b32 v[0:1], v2 offset0:130 offset1:195
	v_add_u32_e32 v2, 0x400, v2
	ds_read2_b32 v[6:7], v2 offset0:4 offset1:69
	ds_read2_b32 v[2:3], v2 offset0:134 offset1:199
	v_lshlrev_b32_e32 v128, 1, v8
	s_waitcnt lgkmcnt(2)
	v_cvt_pk_f16_f32 v1, v0, v1
	v_cvt_pk_f16_f32 v0, v4, v5
	s_waitcnt lgkmcnt(0)
	v_cvt_pk_f16_f32 v3, v2, v3
	v_cvt_pk_f16_f32 v2, v6, v7
	v_add_u32_e32 v6, s84, v9
	v_mov_b64_e32 v[4:5], s[38:39]
	v_mad_i64_i32 v[4:5], s[24:25], v6, s15, v[4:5]
	s_lshl_b32 s84, s2, 1
	v_lshl_add_u64 v[4:5], v[4:5], 0, s[84:85]
	v_lshl_add_u64 v[4:5], v[4:5], 0, v[128:129]
	global_store_dwordx4 v[4:5], v[0:3], off
	s_barrier
	s_mov_b64 s[2:3], 0
.LBB0_119:
	s_andn2_b64 vcc, exec, s[2:3]
	s_cbranch_vccnz .LBB0_121
	s_add_i32 s2, s70, 0xfffff7c0
	s_lshr_b32 s24, s2, 7
	s_add_u32 s2, s50, s24
	s_addc_u32 s3, s45, 0
	v_readlane_b32 s52, v253, 1
	s_lshl_b64 s[2:3], s[2:3], 21
	v_readlane_b32 s60, v253, 9
	v_readlane_b32 s61, v253, 10
	s_add_u32 s25, s60, s2
	s_addc_u32 s33, s61, s3
	s_mul_hi_u32 s3, s24, 0x120000
	s_mul_i32 s24, s24, 0x120000
	v_readlane_b32 s53, v253, 2
	s_add_u32 s2, s43, s24
	s_addc_u32 s3, s44, s3
	s_and_b32 s53, s87, 0x3c0
	v_mov_b32_e32 v8, v208
	s_and_b32 s52, s97, 0x1c0
	s_lshl_b32 s24, s53, 2
	v_ashrrev_i32_e32 v2, 4, v8
	s_add_u32 s24, s25, s24
	v_lshlrev_b32_e32 v0, 4, v8
	v_add_u32_e32 v6, s52, v2
	s_addc_u32 s25, s33, 0
	v_and_b32_e32 v128, 0xf0, v0
	v_ashrrev_i32_e32 v7, 31, v6
	v_lshl_add_u64 v[4:5], s[24:25], 0, v[128:129]
	v_lshlrev_b64 v[0:1], 12, v[6:7]
	s_movk_i32 s5, 0x104
	v_lshl_add_u64 v[0:1], v[4:5], 0, v[0:1]
	v_mul_lo_u32 v2, v2, s5
	v_add3_u32 v7, 0, v128, v2
	global_load_dwordx4 v[0:3], v[0:1], off
	v_add_u32_e32 v10, 32, v6
	v_ashrrev_i32_e32 v11, 31, v10
	v_lshlrev_b64 v[10:11], 12, v[10:11]
	v_lshl_add_u64 v[10:11], v[4:5], 0, v[10:11]
	global_load_dwordx4 v[12:15], v[10:11], off
	v_ashrrev_i32_e32 v9, 3, v8
	s_lshl_b32 s84, s52, 1
	s_movk_i32 s5, 0x7ff
	v_readlane_b32 s54, v253, 3
	v_readlane_b32 s55, v253, 4
	v_readlane_b32 s56, v253, 5
	v_readlane_b32 s57, v253, 6
	v_readlane_b32 s58, v253, 7
	v_readlane_b32 s59, v253, 8
	v_readlane_b32 s62, v253, 11
	v_readlane_b32 s63, v253, 12
	v_readlane_b32 s64, v253, 13
	v_readlane_b32 s65, v253, 14
	v_readlane_b32 s66, v253, 15
	v_readlane_b32 s67, v253, 16
	s_waitcnt vmcnt(0)
	ds_write2_b32 v7, v0, v1 offset1:1
	ds_write2_b32 v7, v2, v3 offset0:2 offset1:3
	v_add_u32_e32 v4, 0x2080, v7
	s_waitcnt vmcnt(0)
	ds_write2_b32 v4, v12, v13 offset1:1
	v_add_u32_e32 v0, 0x2088, v7
	ds_write2_b32 v0, v14, v15 offset1:1
	v_lshlrev_b32_e32 v0, 3, v8
	v_and_b32_e32 v8, 56, v0
	v_lshlrev_b32_e32 v0, 2, v9
	v_mul_u32_u24_e32 v1, 0x104, v8
	v_add3_u32 v2, 0, v0, v1
	s_waitcnt lgkmcnt(0)
	s_barrier
	ds_read2_b32 v[4:5], v2 offset1:65
	ds_read2_b32 v[0:1], v2 offset0:130 offset1:195
	v_add_u32_e32 v2, 0x400, v2
	ds_read2_b32 v[6:7], v2 offset0:4 offset1:69
	ds_read2_b32 v[2:3], v2 offset0:134 offset1:199
	v_lshlrev_b32_e32 v128, 1, v8
	s_waitcnt lgkmcnt(2)
	v_cvt_pk_f16_f32 v1, v0, v1
	v_cvt_pk_f16_f32 v0, v4, v5
	s_waitcnt lgkmcnt(0)
	v_cvt_pk_f16_f32 v3, v2, v3
	v_cvt_pk_f16_f32 v2, v6, v7
	v_add_u32_e32 v6, s53, v9
	v_mov_b64_e32 v[4:5], s[2:3]
	v_mad_i64_i32 v[4:5], s[2:3], v6, s4, v[4:5]
	v_lshl_add_u64 v[4:5], v[4:5], 0, s[84:85]
	v_lshl_add_u64 v[4:5], v[4:5], 0, v[128:129]
	global_store_dwordx4 v[4:5], v[0:3], off
	s_barrier

; DI int otid() { int t = threadIdx.x; asm volatile("" : "+v"(t)); return t; }
; DI void cvt_tile(const float* __restrict__ src, int ldn, h16* __restrict__ dst, int ldk, int k0, int n0, float* t) {
;   const int tid = otid();
;   {
;     const int r = tid >> 4, c4 = tid & 15;
; #pragma unroll
;     for (int i = 0; i < 2; ++i) {
;       const int k = r + 32 * i;
;       const float4 v = *(const float4*)(src + (size_t)(k0 + k) * ldn + n0 + c4 * 4);
;       t[k * 65 + c4 * 4 + 0] = v.x; t[k * 65 + c4 * 4 + 1] = v.y; t[k * 65 + c4 * 4 + 2] = v.z; t[k * 65 + c4 * 4 + 3] = v.w;
;     }
;   }
;   __syncthreads();
;   {
;     const int n = tid >> 3, kc = tid & 7;
;     half8 o;
; #pragma unroll
;     for (int j = 0; j < 8; ++j) o[j] = (h16)t[(kc * 8 + j) * 65 + n];
;     *(half8*)(dst + (size_t)(n0 + n) * ldk + k0 + kc * 8) = o;
;   }
;   __syncthreads();
; }
; DI void cvt_layer_weights(const Params& P, int layer, int t0, int step, char* smem) {
;     ...
;     if (t < 2112) {
;       cvt_tile(P.w_in + (size_t)layer * D * IN_COLS, IN_COLS, winT, LDH, (t & 15) * 64, (t >> 4) * 64, (float*)smem);
.LBB0_122:
	s_andn2_b64 vcc, exec, s[2:3]
	s_cbranch_vccnz .LBB0_115
	s_and_b32 s2, s96, 0xffffffc0
	s_ashr_i32 s3, s2, 31
	s_and_b32 s33, s97, 0x3c0
	v_mov_b32_e32 v6, v208
	s_lshl_b64 s[24:25], s[2:3], 2
	s_add_u32 s24, s76, s24
	v_lshlrev_b32_e32 v0, 4, v6
	v_ashrrev_i32_e32 v2, 4, v6
	s_addc_u32 s25, s77, s25
	v_and_b32_e32 v128, 0xf0, v0
	v_lshl_add_u64 v[4:5], s[24:25], 0, v[128:129]
	v_add_u32_e32 v7, s33, v2
	s_mov_b32 s5, 0x8400
	s_movk_i32 s3, 0x104
	v_mad_i64_i32 v[0:1], s[24:25], v7, s5, v[4:5]
	v_mul_lo_u32 v2, v2, s3
	v_add3_u32 v8, 0, v128, v2
	global_load_dwordx4 v[0:3], v[0:1], off
	v_add_u32_e32 v10, 32, v7
	v_mad_i64_i32 v[10:11], s[24:25], v10, s5, v[4:5]
	global_load_dwordx4 v[12:15], v[10:11], off
	s_lshl_b32 s84, s33, 1
	s_waitcnt vmcnt(0)
	ds_write2_b32 v8, v0, v1 offset1:1
	ds_write2_b32 v8, v2, v3 offset0:2 offset1:3
	v_add_u32_e32 v4, 0x2080, v8
	s_movk_i32 s5, 0x7ff
	s_waitcnt vmcnt(0)
	ds_write2_b32 v4, v12, v13 offset1:1
	v_add_u32_e32 v0, 0x2088, v8
	ds_write2_b32 v0, v14, v15 offset1:1
	v_lshlrev_b32_e32 v0, 3, v6
	v_ashrrev_i32_e32 v8, 3, v6
	v_and_b32_e32 v9, 56, v0
	v_lshlrev_b32_e32 v0, 2, v8
	v_mul_u32_u24_e32 v1, 0x104, v9
	v_add3_u32 v2, 0, v0, v1
	s_waitcnt lgkmcnt(0)
	s_barrier
	ds_read2_b32 v[4:5], v2 offset1:65
	ds_read2_b32 v[0:1], v2 offset0:130 offset1:195
	v_add_u32_e32 v2, 0x400, v2
	ds_read2_b32 v[6:7], v2 offset0:4 offset1:69
	ds_read2_b32 v[2:3], v2 offset0:134 offset1:199
	v_lshlrev_b32_e32 v128, 1, v9
	s_waitcnt lgkmcnt(2)
	v_cvt_pk_f16_f32 v1, v0, v1
	v_cvt_pk_f16_f32 v0, v4, v5
	s_waitcnt lgkmcnt(0)
	v_cvt_pk_f16_f32 v3, v2, v3
	v_cvt_pk_f16_f32 v2, v6, v7
	v_add_u32_e32 v6, s2, v8
	v_mov_b64_e32 v[4:5], s[0:1]
	v_mad_i64_i32 v[4:5], s[2:3], v6, s15, v[4:5]
	v_lshl_add_u64 v[4:5], v[4:5], 0, s[84:85]
	v_lshl_add_u64 v[4:5], v[4:5], 0, v[128:129]
	global_store_dwordx4 v[4:5], v[0:3], off
	s_barrier
	s_branch .LBB0_115
